# loop-edge edit: attn task loop drops two redundant workgroup barriers (after the queue-slot read, and the diff task's trailing one adjacent to the loop's own)
# baseline (speedup 1.0000x reference)
.LBB0_216:
	s_or_b64 exec, exec, s[4:5]
	s_waitcnt lgkmcnt(0)
.LBB0_217:
	s_or_b64 exec, exec, s[8:9]
	s_xor_b64 s[4:5], exec, -1
	s_barrier

.LBB0_223:
	s_or_b64 exec, exec, s[4:5]
	s_add_i32 s0, 0, 0x24000
	s_mov_b64 s[4:5], src_shared_base
	s_cmp_lg_u32 s0, -1
	s_cselect_b32 s0, s0, 0
	s_cselect_b32 s4, s5, 0
	v_mov_b32_e32 v4, s0
	v_mov_b32_e32 v5, s4
	s_waitcnt lgkmcnt(0)
	s_barrier
	ds_read_b32 v4, v4
	s_movk_i32 s0, 0x548
	s_mov_b64 s[4:5], -1
	s_waitcnt lgkmcnt(0)
	v_cmp_gt_i32_e32 vcc, s0, v4
	s_mov_b64 s[6:7], exec
	v_writelane_b32 v254, s6, 48
	s_nop 1
	v_writelane_b32 v254, s7, 49
	s_and_b64 s[6:7], s[6:7], vcc
	s_mov_b64 exec, s[6:7]
	s_cbranch_execz .LBB0_218
	v_ashrrev_i32_e32 v5, 31, v4
	s_getpc_b64 s[4:5]
	s_add_u32 s4, s4, _ZL5g_tab@rel32@lo+8
	s_addc_u32 s5, s5, _ZL5g_tab@rel32@hi+16
	v_lshl_add_u64 v[4:5], v[4:5], 2, s[4:5]
	global_load_dword v10, v[4:5], off
	s_mov_b32 s0, 0x10000
	s_waitcnt vmcnt(0)
	v_cmp_gt_u32_e64 s[4:5], s0, v10
	s_nop 1
	v_writelane_b32 v254, s4, 50
	s_mov_b32 s0, 0xffff
	v_cmp_lt_u32_e64 s[6:7], s0, v10
	v_writelane_b32 v254, s5, 51
	v_cmp_ne_u32_sdwa s[4:5], v10, v206 src0_sel:WORD_1 src1_sel:DWORD
	v_writelane_b32 v254, s6, 52
	v_and_b32_e32 v12, 0xffff, v10
	s_and_b64 s[4:5], s[6:7], s[4:5]
	v_writelane_b32 v254, s7, 53
	s_and_saveexec_b64 s[6:7], s[4:5]
	s_xor_b64 s[6:7], exec, s[6:7]
	v_writelane_b32 v254, s6, 54
	s_nop 1
	v_writelane_b32 v254, s7, 55
	s_cbranch_execz .LBB0_314
	v_cmp_gt_i16_sdwa s[6:7], v10, v206 src0_sel:WORD_1 src1_sel:DWORD
	s_mov_b64 s[8:9], 0
	s_mov_b64 s[4:5], 0
	s_and_saveexec_b64 s[10:11], s[6:7]
	s_xor_b64 s[6:7], exec, s[10:11]
	s_cbranch_execz .LBB0_228
	v_mov_b32_e32 v0, 3
	v_cmp_ne_u16_sdwa s[4:5], v10, v0 src0_sel:WORD_1 src1_sel:DWORD
	s_and_b64 s[8:9], s[4:5], exec
	s_mov_b64 s[4:5], exec
	s_andn2_saveexec_b64 s[6:7], s[6:7]
	s_cbranch_execnz .LBB0_229
